# NSA selected-branch fast path: PV second half split so pa2 MFMAs run first with the pa3 sums/cvt/masks in their shadow; pa2 cvt moved under first-half PV MFMAs
# baseline (speedup 1.0000x reference)
.Lsel_fast2:
	v_add_u32_e32 v0, s91, v184
	ds_read_b128 v[2:5], v0
	v_add_u32_e32 v0, s91, v185
	ds_read_b128 v[208:211], v0
	v_add_u32_e32 v0, s91, v186
	ds_read_b128 v[212:215], v0
	v_add_u32_e32 v0, s91, v183
	ds_read_b128 v[216:219], v0
	s_waitcnt lgkmcnt(3)
	v_mfma_f32_32x32x16_bf16 v[80:95], v[2:5], v[140:143], 0
	v_add_u32_e32 v0, s91, v182
	ds_read_b128 v[2:5], v0
	s_waitcnt lgkmcnt(3)
	v_mfma_f32_32x32x16_bf16 v[80:95], v[208:211], v[136:139], v[80:95]
	v_add_u32_e32 v0, s91, v181
	ds_read_b128 v[208:211], v0
	s_waitcnt lgkmcnt(3)
	v_mfma_f32_32x32x16_bf16 v[80:95], v[212:215], v[132:135], v[80:95]
	v_add_u32_e32 v0, s91, v180
	ds_read_b128 v[212:215], v0
	s_waitcnt lgkmcnt(3)
	v_mfma_f32_32x32x16_bf16 v[80:95], v[216:219], v[128:131], v[80:95]
	v_add_u32_e32 v0, s91, v179
	ds_read_b128 v[216:219], v0
	s_waitcnt lgkmcnt(3)
	v_mfma_f32_32x32x16_bf16 v[80:95], v[2:5], v[124:127], v[80:95]
	v_add_u32_e32 v0, s91, v184
	ds_read_b128 v[2:5], v0 offset:8192
	s_waitcnt lgkmcnt(3)
	v_mfma_f32_32x32x16_bf16 v[80:95], v[208:211], v[120:123], v[80:95]
	v_add_u32_e32 v0, s91, v185
	ds_read_b128 v[208:211], v0 offset:8192
	s_waitcnt lgkmcnt(3)
	v_mfma_f32_32x32x16_bf16 v[80:95], v[212:215], v[116:119], v[80:95]
	v_add_u32_e32 v0, s91, v186
	ds_read_b128 v[212:215], v0 offset:8192
	s_waitcnt lgkmcnt(3)
	v_mfma_f32_32x32x16_bf16 v[80:95], v[216:219], v[112:115], v[80:95]
	v_add_u32_e32 v0, s91, v183
	ds_read_b128 v[216:219], v0 offset:8192
	s_waitcnt lgkmcnt(3)
	v_mfma_f32_32x32x16_bf16 v[96:111], v[2:5], v[140:143], 0
	v_add_u32_e32 v0, s91, v182
	ds_read_b128 v[2:5], v0 offset:8192
	s_waitcnt lgkmcnt(3)
	v_mfma_f32_32x32x16_bf16 v[96:111], v[208:211], v[136:139], v[96:111]
	v_add_u32_e32 v0, s91, v181
	ds_read_b128 v[208:211], v0 offset:8192
	s_waitcnt lgkmcnt(3)
	v_mfma_f32_32x32x16_bf16 v[96:111], v[212:215], v[132:135], v[96:111]
	v_add_u32_e32 v0, s91, v180
	ds_read_b128 v[212:215], v0 offset:8192
	s_waitcnt lgkmcnt(3)
	v_mfma_f32_32x32x16_bf16 v[96:111], v[216:219], v[128:131], v[96:111]
	v_add_u32_e32 v0, s91, v179
	ds_read_b128 v[216:219], v0 offset:8192
	v_exp_f32_e32 v80, v80
	v_exp_f32_e32 v81, v81
	v_exp_f32_e32 v82, v82
	s_waitcnt lgkmcnt(3)
	v_mfma_f32_32x32x16_bf16 v[96:111], v[2:5], v[124:127], v[96:111]
	v_exp_f32_e32 v83, v83
	v_exp_f32_e32 v84, v84
	v_exp_f32_e32 v85, v85
	s_waitcnt lgkmcnt(2)
	v_mfma_f32_32x32x16_bf16 v[96:111], v[208:211], v[120:123], v[96:111]
	v_exp_f32_e32 v86, v86
	v_exp_f32_e32 v87, v87
	v_exp_f32_e32 v88, v88
	s_waitcnt lgkmcnt(1)
	v_mfma_f32_32x32x16_bf16 v[96:111], v[212:215], v[116:119], v[96:111]
	v_exp_f32_e32 v89, v89
	v_exp_f32_e32 v90, v90
	v_exp_f32_e32 v91, v91
	s_waitcnt lgkmcnt(0)
	v_mfma_f32_32x32x16_bf16 v[96:111], v[216:219], v[112:115], v[96:111]
	v_exp_f32_e32 v92, v92
	v_exp_f32_e32 v93, v93
	v_exp_f32_e32 v94, v94
	v_exp_f32_e32 v95, v95
	v_add_u32_e32 v207, s91, v153
	v_add3_u32 v0, v207, v199, v178
	v_add_u32_e32 v6, s91, v200
	v_add3_u32 v6, v6, v178, v153
	v_add3_u32 v7, v207, v201, v178
	v_add_u32_e32 v230, s91, v202
	v_add3_u32 v230, v230, v178, v153
	ds_read_b64_tr_b16 v[12:13], v0 offset:32768
	ds_read_b64_tr_b16 v[14:15], v6 offset:34816
	ds_read_b64_tr_b16 v[208:209], v0 offset:36864
	ds_read_b64_tr_b16 v[210:211], v6 offset:38912
	ds_read_b64_tr_b16 v[212:213], v7 offset:32768
	ds_read_b64_tr_b16 v[214:215], v230 offset:34816
	ds_read_b64_tr_b16 v[216:217], v7 offset:36864
	ds_read_b64_tr_b16 v[218:219], v230 offset:38912
	v_add3_u32 v231, v207, v203, v178
	v_add_u32_e32 v241, s91, v204
	v_add3_u32 v241, v241, v178, v153
	v_add3_u32 v242, v207, v205, v178
	v_add_u32_e32 v243, s91, v206
	v_add3_u32 v243, v243, v178, v153
	s_nop 0
	v_pk_add_f32 v[244:245], v[80:81], v[82:83]
	v_pk_add_f32 v[246:247], v[84:85], v[86:87]
	v_pk_add_f32 v[232:233], v[88:89], v[90:91]
	v_pk_add_f32 v[234:235], v[92:93], v[94:95]
	v_pk_add_f32 v[244:245], v[244:245], v[246:247]
	v_pk_add_f32 v[232:233], v[232:233], v[234:235]
	v_pk_add_f32 v[244:245], v[244:245], v[232:233]
	v_add_f32_e32 v240, v244, v245
	v_cvt_pk_bf16_f32 v8, v80, v81
	v_cvt_pk_bf16_f32 v9, v82, v83
	v_cvt_pk_bf16_f32 v10, v84, v85
	v_cvt_pk_bf16_f32 v11, v86, v87
	v_cvt_pk_bf16_f32 v88, v88, v89
	v_cvt_pk_bf16_f32 v89, v90, v91
	v_cvt_pk_bf16_f32 v90, v92, v93
	v_cvt_pk_bf16_f32 v91, v94, v95
	v_cndmask_b32_e64 v8, 0, v8, s[72:73]
	v_cndmask_b32_e64 v9, 0, v9, s[72:73]
	v_cndmask_b32_e64 v10, 0, v10, s[72:73]
	v_cndmask_b32_e64 v11, 0, v11, s[72:73]
	v_cndmask_b32_e64 v88, 0, v88, s[72:73]
	v_cndmask_b32_e64 v89, 0, v89, s[72:73]
	v_cndmask_b32_e64 v90, 0, v90, s[72:73]
	v_cndmask_b32_e64 v91, 0, v91, s[72:73]
	ds_read_b64_tr_b16 v[80:81], v231 offset:32768
	ds_read_b64_tr_b16 v[82:83], v241 offset:34816
	ds_read_b64_tr_b16 v[84:85], v231 offset:36864
	ds_read_b64_tr_b16 v[86:87], v241 offset:38912
	ds_read_b64_tr_b16 v[92:93], v242 offset:32768
	ds_read_b64_tr_b16 v[94:95], v243 offset:34816
	ds_read_b64_tr_b16 v[236:237], v242 offset:36864
	ds_read_b64_tr_b16 v[238:239], v243 offset:38912
	s_waitcnt lgkmcnt(8)
	v_mfma_f32_32x32x16_bf16 v[64:79], v[8:11], v[12:15], v[64:79]
	v_exp_f32_e32 v96, v96
	v_exp_f32_e32 v97, v97
	v_mfma_f32_32x32x16_bf16 v[64:79], v[88:91], v[208:211], v[64:79]
	v_exp_f32_e32 v98, v98
	v_exp_f32_e32 v99, v99
	ds_read_b64_tr_b16 v[12:13], v0 offset:40960
	ds_read_b64_tr_b16 v[14:15], v6 offset:43008
	ds_read_b64_tr_b16 v[208:209], v0 offset:45056
	ds_read_b64_tr_b16 v[210:211], v6 offset:47104
	v_mfma_f32_32x32x16_bf16 v[48:63], v[8:11], v[212:215], v[48:63]
	v_exp_f32_e32 v100, v100
	v_exp_f32_e32 v101, v101
	v_mfma_f32_32x32x16_bf16 v[48:63], v[88:91], v[216:219], v[48:63]
	v_exp_f32_e32 v102, v102
	v_exp_f32_e32 v103, v103
	ds_read_b64_tr_b16 v[212:213], v7 offset:40960
	ds_read_b64_tr_b16 v[214:215], v230 offset:43008
	ds_read_b64_tr_b16 v[216:217], v7 offset:45056
	ds_read_b64_tr_b16 v[218:219], v230 offset:47104
	s_waitcnt lgkmcnt(8)
	v_mfma_f32_32x32x16_bf16 v[32:47], v[8:11], v[80:83], v[32:47]
	v_exp_f32_e32 v104, v104
	v_exp_f32_e32 v105, v105
	v_cvt_pk_bf16_f32 v2, v96, v97
	v_cvt_pk_bf16_f32 v3, v98, v99
	v_mfma_f32_32x32x16_bf16 v[32:47], v[88:91], v[84:87], v[32:47]
	v_exp_f32_e32 v106, v106
	v_exp_f32_e32 v107, v107
	v_cvt_pk_bf16_f32 v4, v100, v101
	v_cvt_pk_bf16_f32 v5, v102, v103
	ds_read_b64_tr_b16 v[80:81], v231 offset:40960
	ds_read_b64_tr_b16 v[82:83], v241 offset:43008
	ds_read_b64_tr_b16 v[84:85], v231 offset:45056
	ds_read_b64_tr_b16 v[86:87], v241 offset:47104
	v_mfma_f32_32x32x16_bf16 v[16:31], v[8:11], v[92:95], v[16:31]
	v_exp_f32_e32 v108, v108
	v_exp_f32_e32 v109, v109
	v_cndmask_b32_e64 v2, 0, v2, s[72:73]
	v_cndmask_b32_e64 v3, 0, v3, s[72:73]
	v_mfma_f32_32x32x16_bf16 v[16:31], v[88:91], v[236:239], v[16:31]
	v_exp_f32_e32 v110, v110
	v_exp_f32_e32 v111, v111
	v_cndmask_b32_e64 v4, 0, v4, s[72:73]
	v_cndmask_b32_e64 v5, 0, v5, s[72:73]
	ds_read_b64_tr_b16 v[92:93], v242 offset:40960
	ds_read_b64_tr_b16 v[94:95], v243 offset:43008
	ds_read_b64_tr_b16 v[236:237], v242 offset:45056
	ds_read_b64_tr_b16 v[238:239], v243 offset:47104
	s_waitcnt lgkmcnt(14)
	v_mfma_f32_32x32x16_bf16 v[64:79], v[2:5], v[12:15], v[64:79]
	v_pk_add_f32 v[244:245], v[96:97], v[98:99]
	v_pk_add_f32 v[246:247], v[100:101], v[102:103]
	v_pk_add_f32 v[6:7], v[104:105], v[106:107]
	v_pk_add_f32 v[230:231], v[108:109], v[110:111]
	s_waitcnt lgkmcnt(10)
	v_mfma_f32_32x32x16_bf16 v[48:63], v[2:5], v[212:215], v[48:63]
	v_pk_add_f32 v[244:245], v[244:245], v[246:247]
	v_pk_add_f32 v[6:7], v[6:7], v[230:231]
	v_pk_add_f32 v[244:245], v[244:245], v[6:7]
	v_add_f32_e32 v244, v244, v245
	s_waitcnt lgkmcnt(6)
	v_mfma_f32_32x32x16_bf16 v[32:47], v[2:5], v[80:83], v[32:47]
	v_cvt_pk_bf16_f32 v232, v104, v105
	v_cvt_pk_bf16_f32 v233, v106, v107
	v_cvt_pk_bf16_f32 v234, v108, v109
	v_cvt_pk_bf16_f32 v235, v110, v111
	s_waitcnt lgkmcnt(2)
	v_mfma_f32_32x32x16_bf16 v[16:31], v[2:5], v[92:95], v[16:31]
	v_cndmask_b32_e64 v232, 0, v232, s[72:73]
	v_cndmask_b32_e64 v233, 0, v233, s[72:73]
	v_cndmask_b32_e64 v234, 0, v234, s[72:73]
	v_cndmask_b32_e64 v235, 0, v235, s[72:73]
	v_add_f32_e32 v240, v240, v244
	v_cndmask_b32_e64 v240, 0, v240, s[72:73]
	v_add_f32_e32 v198, v198, v240
	s_waitcnt lgkmcnt(0)
	v_mfma_f32_32x32x16_bf16 v[64:79], v[232:235], v[208:211], v[64:79]
	v_mfma_f32_32x32x16_bf16 v[48:63], v[232:235], v[216:219], v[48:63]
	v_mfma_f32_32x32x16_bf16 v[32:47], v[232:235], v[84:87], v[32:47]
	v_mfma_f32_32x32x16_bf16 v[16:31], v[232:235], v[236:239], v[16:31]
	s_branch .LBB0_743
